# c21 + pass C: next-unit L2 touch re-added but issued after the unit's last counted wait into a private register (no wait ever covers it)
# speedup vs baseline: 1.0057x; 1.0043x over previous
.LBB0_1225:
	s_or_b64 exec, exec, s[0:1]
	v_mov_b64_e32 v[104:105], v[24:25]
	s_mov_b32 s85, 1
	s_branch .LBB0_1227
.LBB0_1226:
	v_mov_b32_e32 v26, 0
	s_mov_b32 s85, 0
.LBB0_1227:
	v_and_b32_e32 v24, -4, v57
	v_and_b32_e32 v36, 15, v53
	v_add_u32_e32 v27, s59, v24
	v_or_b32_e32 v38, s56, v36
	v_lshlrev_b32_e32 v34, 6, v27
	s_waitcnt vmcnt(0)
	v_or_b32_e32 v32, 0x1000, v38
	v_add_u32_e32 v24, v34, v32
	v_or_b32_e32 v40, 64, v34
	v_or_b32_e32 v41, 0x80, v34
	v_or_b32_e32 v42, 0xc0, v34
	v_or_b32_e32 v43, 0x1010, v38
	v_ashrrev_i32_e32 v25, 31, v24
	v_add_u32_e32 v28, v40, v32
	v_add_u32_e32 v30, v41, v32
	v_add_u32_e32 v32, v42, v32
	v_add_u32_e32 v34, v34, v43
	v_lshl_add_u64 v[24:25], v[24:25], 1, s[42:43]
	v_ashrrev_i32_e32 v29, 31, v28
	v_ashrrev_i32_e32 v31, 31, v30
	v_ashrrev_i32_e32 v33, 31, v32
	v_ashrrev_i32_e32 v35, 31, v34
	v_lshl_add_u64 v[28:29], v[28:29], 1, s[42:43]
	v_lshl_add_u64 v[30:31], v[30:31], 1, s[42:43]
	v_lshl_add_u64 v[32:33], v[32:33], 1, s[42:43]
	v_lshl_add_u64 v[34:35], v[34:35], 1, s[42:43]
	global_load_ushort v50, v[24:25], off
	global_load_ushort v54, v[28:29], off
	global_load_ushort v67, v[30:31], off
	global_load_ushort v70, v[32:33], off
	global_load_ushort v71, v[34:35], off
	v_add_u32_e32 v24, v40, v43
	v_ashrrev_i32_e32 v25, 31, v24
	v_add_u32_e32 v28, v41, v43
	v_add_u32_e32 v30, v42, v43
	v_lshl_add_u64 v[24:25], v[24:25], 1, s[42:43]
	v_ashrrev_i32_e32 v29, 31, v28
	v_ashrrev_i32_e32 v31, 31, v30
	v_lshl_add_u64 v[28:29], v[28:29], 1, s[42:43]
	v_lshl_add_u64 v[30:31], v[30:31], 1, s[42:43]
	global_load_ushort v25, v[24:25], off
	s_nop 0
	global_load_ushort v72, v[28:29], off
	global_load_ushort v73, v[30:31], off
	v_ashrrev_i32_e32 v24, 1, v53
	v_and_b32_e32 v28, -8, v24
	v_or_b32_e32 v74, s59, v36
	v_lshlrev_b32_e32 v24, 2, v28
	v_lshlrev_b32_e32 v29, 2, v36
	v_mul_lo_u32 v28, v28, s62
	v_add3_u32 v36, s16, v28, v29
	v_add_u32_e32 v44, 0x4000, v36
	v_add_u32_e32 v68, 0x4800, v36
	v_lshl_add_u32 v27, v27, 6, v27
	s_mov_b32 s4, 0
	s_mov_b32 s5, s80
	s_waitcnt vmcnt(2)
	v_mad_u64_u32 v[48:49], s[0:1], v74, s62, v[24:25]
	ds_read2_b32 v[28:29], v48 offset1:1
	ds_read2_b32 v[30:31], v48 offset0:2 offset1:3
	ds_read2_b32 v[32:33], v48 offset0:4 offset1:5
	ds_read2_b32 v[34:35], v48 offset0:6 offset1:7
	v_add_u32_e32 v49, 0x4400, v36
	ds_read2_b32 v[60:61], v48 offset0:32 offset1:33
	ds_read2_b32 v[40:41], v44 offset0:64 offset1:80
	ds_read2_b32 v[42:43], v44 offset0:129 offset1:145
	ds_read2_b32 v[44:45], v44 offset0:194 offset1:210
	ds_read2_b32 v[46:47], v49 offset0:3 offset1:19
	ds_read2_b32 v[56:57], v49 offset0:68 offset1:84
	ds_read2_b32 v[58:59], v49 offset0:133 offset1:149
	ds_read2_b32 v[62:63], v49 offset0:198 offset1:214
	ds_read2_b32 v[68:69], v68 offset0:7 offset1:23
	s_waitcnt lgkmcnt(12)
	v_cvt_pk_bf16_f32 v28, v28, v29
	s_waitcnt lgkmcnt(11)
	v_cvt_pk_bf16_f32 v29, v30, v31
	s_waitcnt lgkmcnt(10)
	v_cvt_pk_bf16_f32 v30, v32, v33
	s_waitcnt lgkmcnt(9)
	v_cvt_pk_bf16_f32 v31, v34, v35
	s_waitcnt lgkmcnt(6)
	v_cvt_pk_bf16_f32 v32, v40, v42
	v_cvt_pk_bf16_f32 v40, v41, v43
	s_waitcnt lgkmcnt(4)
	v_cvt_pk_bf16_f32 v33, v44, v46
	v_cvt_pk_bf16_f32 v41, v45, v47
	s_waitcnt lgkmcnt(2)
	v_cvt_pk_bf16_f32 v34, v56, v58
	v_cvt_pk_bf16_f32 v42, v57, v59
	s_waitcnt lgkmcnt(0)
	v_cvt_pk_bf16_f32 v35, v62, v68
	v_cvt_pk_bf16_f32 v43, v63, v69
	v_lshlrev_b32_e32 v44, 16, v50
	v_lshlrev_b32_e32 v45, 16, v54
	v_lshlrev_b32_e32 v46, 16, v67
	v_lshlrev_b32_e32 v47, 16, v70
	v_lshlrev_b32_e32 v56, 16, v71
	v_lshlrev_b32_e32 v57, 16, v25
	s_waitcnt vmcnt(1)
	v_lshlrev_b32_e32 v58, 16, v72
	s_waitcnt vmcnt(0)
	v_lshlrev_b32_e32 v59, 16, v73
	v_add_u32_e32 v25, 0x6000, v36
	v_mfma_f32_16x16x32_bf16 v[32:35], v[28:31], v[32:35], v[44:47]
	v_mfma_f32_16x16x32_bf16 v[28:31], v[28:31], v[40:43], v[56:59]
	s_nop 1
	ds_read2_b32 v[44:45], v25 offset0:96 offset1:112
	ds_read2_b32 v[46:47], v25 offset0:161 offset1:177
	ds_read2_b32 v[42:43], v48 offset0:34 offset1:35
	ds_read2_b32 v[56:57], v48 offset0:36 offset1:37
	ds_read2_b32 v[48:49], v48 offset0:38 offset1:39
	ds_read2_b32 v[58:59], v25 offset0:226 offset1:242
	v_add_u32_e32 v25, 0x6400, v36
	v_cvt_pk_bf16_f32 v40, v60, v61
	ds_read2_b32 v[60:61], v25 offset0:35 offset1:51
	ds_read2_b32 v[62:63], v25 offset0:100 offset1:116
	ds_read2_b32 v[68:69], v25 offset0:165 offset1:181
	ds_read2_b32 v[70:71], v25 offset0:230 offset1:246
	v_add_u32_e32 v25, 0x6800, v36
	ds_read2_b32 v[72:73], v25 offset0:39 offset1:55
	s_waitcnt lgkmcnt(8)
	v_cvt_pk_bf16_f32 v41, v42, v43
	s_waitcnt lgkmcnt(7)
	v_cvt_pk_bf16_f32 v42, v56, v57
	s_waitcnt lgkmcnt(6)
	v_cvt_pk_bf16_f32 v43, v48, v49
	v_cvt_pk_bf16_f32 v44, v44, v46
	v_cvt_pk_bf16_f32 v56, v45, v47
	s_waitcnt lgkmcnt(4)
	v_cvt_pk_bf16_f32 v45, v58, v60
	s_waitcnt lgkmcnt(2)
	v_cvt_pk_bf16_f32 v46, v62, v68
	s_waitcnt lgkmcnt(0)
	v_cvt_pk_bf16_f32 v47, v70, v72
	v_cvt_pk_bf16_f32 v57, v59, v61
	v_cvt_pk_bf16_f32 v58, v63, v69
	v_mfma_f32_16x16x32_bf16 v[32:35], v[40:43], v[44:47], v[32:35]
	v_cvt_pk_bf16_f32 v59, v71, v73
	v_add_lshl_u32 v36, v27, v38, 2
	v_add_u32_e32 v25, 0x8200, v36
	v_mfma_f32_16x16x32_bf16 v[28:31], v[40:43], v[56:59], v[28:31]
	v_or_b32_e32 v49, 16, v38
	s_nop 2
	ds_write2_b32 v25, v33, v34 offset0:65 offset1:130
	ds_write_b32 v36, v35 offset:34060
	v_add_u32_e32 v25, 0x8000, v36
	v_add_lshl_u32 v50, v27, v49, 2
	ds_write2_b32 v25, v32, v28 offset0:128 offset1:144
	v_add_u32_e32 v25, 0x8200, v50
	ds_write2_b32 v25, v29, v30 offset0:65 offset1:130
	ds_write_b32 v50, v31 offset:34060
	v_mad_u64_u32 v[24:25], s[0:1], v74, s65, v[24:25]
	ds_read_b128 v[28:31], v24 offset:49920
	ds_read_b128 v[32:35], v24 offset:49936
	ds_read_b128 v[40:43], v24 offset:50048
	ds_read_b128 v[44:47], v24 offset:50064
	ds_read_b128 v[56:59], v24 offset:50192
	s_waitcnt lgkmcnt(4)
	v_cvt_pk_bf16_f32 v28, v28, v29
	v_cvt_pk_bf16_f32 v29, v30, v31
	s_waitcnt lgkmcnt(3)
	v_cvt_pk_bf16_f32 v30, v32, v33
	v_cvt_pk_bf16_f32 v31, v34, v35
	s_waitcnt lgkmcnt(2)
	v_cvt_pk_bf16_f32 v40, v40, v41
	v_cvt_pk_bf16_f32 v41, v42, v43
	s_waitcnt lgkmcnt(1)
	v_cvt_pk_bf16_f32 v42, v44, v45
	v_cvt_pk_bf16_f32 v43, v46, v47
	ds_read_b128 v[44:47], v24 offset:50176
	v_mfma_f32_16x16x32_bf16 v[32:35], v[28:31], v[0:3], 0
	v_add_u32_e32 v25, 0x41, v27
	v_add_u32_e32 v54, v25, v38
	v_add_u32_e32 v24, 0x82, v27
	v_mfma_f32_16x16x32_bf16 v[28:31], v[28:31], v[4:7], 0
	s_waitcnt lgkmcnt(0)
	v_cvt_pk_bf16_f32 v44, v44, v45
	v_cvt_pk_bf16_f32 v45, v46, v47
	v_cvt_pk_bf16_f32 v46, v56, v57
	v_cvt_pk_bf16_f32 v47, v58, v59
	v_mfma_f32_16x16x32_bf16 v[32:35], v[40:43], v[8:11], v[32:35]
	v_add_u32_e32 v36, 0x18600, v36
	v_add_u32_e32 v27, 0xc3, v27
	v_add_u32_e32 v48, s71, v53
	v_mfma_f32_16x16x32_bf16 v[28:31], v[40:43], v[12:15], v[28:31]
	v_add_u32_e32 v40, v24, v38
	v_add_u32_e32 v38, v27, v38
	v_add_u32_e32 v24, v24, v49
	v_mfma_f32_16x16x32_bf16 v[32:35], v[44:47], v[16:19], v[32:35]
	v_add_u32_e32 v25, v25, v49
	v_add_u32_e32 v27, v27, v49
	v_lshl_add_u32 v24, v24, 2, v66
	v_mfma_f32_16x16x32_bf16 v[28:31], v[44:47], v[20:23], v[28:31]
	s_lshl_b32 s0, s70, 2
	s_nop 2
	ds_write_b32 v36, v32
	v_lshl_add_u32 v32, v54, 2, v66
	ds_write_b32 v32, v33
	v_lshl_add_u32 v32, v40, 2, v66
	ds_write_b32 v32, v34
	v_lshl_add_u32 v32, v38, 2, v66
	ds_write_b32 v32, v35
	v_lshl_add_u32 v25, v25, 2, v66
	ds_write_b32 v24, v30
	v_lshl_add_u32 v24, v27, 2, v66
	s_add_u32 s0, s60, s0
	v_ashrrev_i32_e32 v49, 31, v48
	v_add_u32_e32 v32, 0x18600, v50
	ds_write_b32 v25, v29
	ds_write_b32 v24, v31
	s_addc_u32 s1, s61, 0
	v_lshl_add_u64 v[24:25], v[48:49], 1, s[28:29]
	v_lshl_add_u32 v27, v53, 2, s33
	v_and_b32_e32 v101, 7, v53
	s_add_i32 s12, s68, s80
	v_lshl_add_u32 v101, v101, 3, s12
	s_add_i32 s12, s68, s69
	s_add_i32 s12, s12, -1
	v_min_u32_e32 v101, s12, v101
	v_lshlrev_b32_e32 v101, 5, v101
	global_load_dword v100, v101, s[0:1]
	ds_write_b32 v32, v28
	s_waitcnt lgkmcnt(0)
	s_barrier
	s_waitcnt vmcnt(0)
	s_cmp_eq_u32 s85, 0
	s_cbranch_scc1 .Lpct_a
	global_load_dword v106, v[104:105], off
.Lpct_a:
	s_branch .LBB0_1229

.LBB0_1394:
	v_and_b32_e32 v24, -4, v59
	v_and_b32_e32 v34, 15, v53
	v_add_u32_e32 v27, s59, v24
	v_or_b32_e32 v40, s56, v34
	s_waitcnt vmcnt(0)
	v_lshlrev_b32_e32 v36, 6, v27
	v_or_b32_e32 v32, 0x1000, v40
	v_add_u32_e32 v24, v36, v32
	v_or_b32_e32 v38, 64, v36
	v_or_b32_e32 v39, 0x80, v36
	v_or_b32_e32 v42, 0xc0, v36
	v_or_b32_e32 v43, 0x1010, v40
	v_ashrrev_i32_e32 v25, 31, v24
	v_add_u32_e32 v28, v38, v32
	v_add_u32_e32 v30, v39, v32
	v_add_u32_e32 v32, v42, v32
	v_add_u32_e32 v36, v36, v43
	v_lshl_add_u64 v[24:25], v[24:25], 1, s[42:43]
	v_ashrrev_i32_e32 v29, 31, v28
	v_ashrrev_i32_e32 v31, 31, v30
	v_ashrrev_i32_e32 v33, 31, v32
	v_ashrrev_i32_e32 v37, 31, v36
	v_lshl_add_u64 v[28:29], v[28:29], 1, s[42:43]
	v_lshl_add_u64 v[30:31], v[30:31], 1, s[42:43]
	v_lshl_add_u64 v[32:33], v[32:33], 1, s[42:43]
	v_lshl_add_u64 v[36:37], v[36:37], 1, s[42:43]
	global_load_ushort v50, v[24:25], off
	global_load_ushort v54, v[28:29], off
	global_load_ushort v67, v[30:31], off
	global_load_ushort v70, v[32:33], off
	global_load_ushort v71, v[36:37], off
	v_add_u32_e32 v24, v38, v43
	v_ashrrev_i32_e32 v25, 31, v24
	v_add_u32_e32 v28, v39, v43
	v_add_u32_e32 v30, v42, v43
	v_lshl_add_u64 v[24:25], v[24:25], 1, s[42:43]
	v_ashrrev_i32_e32 v29, 31, v28
	v_ashrrev_i32_e32 v31, 31, v30
	v_lshl_add_u64 v[28:29], v[28:29], 1, s[42:43]
	v_lshl_add_u64 v[30:31], v[30:31], 1, s[42:43]
	global_load_ushort v25, v[24:25], off
	s_nop 0
	global_load_ushort v72, v[28:29], off
	global_load_ushort v73, v[30:31], off
	v_ashrrev_i32_e32 v24, 1, v53
	v_and_b32_e32 v28, -8, v24
	v_or_b32_e32 v74, s59, v34
	v_lshlrev_b32_e32 v24, 2, v28
	v_lshlrev_b32_e32 v29, 2, v34
	v_mul_lo_u32 v28, v28, s62
	v_add3_u32 v34, s16, v28, v29
	v_add_u32_e32 v62, 0x4400, v34
	v_add_u32_e32 v68, 0x4800, v34
	v_lshl_add_u32 v27, v27, 6, v27
	s_waitcnt vmcnt(2)
	v_mad_u64_u32 v[32:33], s[0:1], v74, s62, v[24:25]
	ds_read2_b32 v[28:29], v32 offset1:1
	ds_read2_b32 v[30:31], v32 offset0:2 offset1:3
	ds_read2_b32 v[36:37], v32 offset0:4 offset1:5
	ds_read2_b32 v[38:39], v32 offset0:6 offset1:7
	v_add_u32_e32 v33, 0x4000, v34
	ds_read2_b32 v[60:61], v32 offset0:32 offset1:33
	ds_read2_b32 v[42:43], v33 offset0:64 offset1:80
	ds_read2_b32 v[44:45], v33 offset0:129 offset1:145
	ds_read2_b32 v[46:47], v33 offset0:194 offset1:210
	ds_read2_b32 v[48:49], v62 offset0:3 offset1:19
	ds_read2_b32 v[56:57], v62 offset0:68 offset1:84
	ds_read2_b32 v[58:59], v62 offset0:133 offset1:149
	ds_read2_b32 v[62:63], v62 offset0:198 offset1:214
	ds_read2_b32 v[68:69], v68 offset0:7 offset1:23
	s_waitcnt lgkmcnt(12)
	v_cvt_pk_bf16_f32 v28, v28, v29
	s_waitcnt lgkmcnt(11)
	v_cvt_pk_bf16_f32 v29, v30, v31
	s_waitcnt lgkmcnt(10)
	v_cvt_pk_bf16_f32 v30, v36, v37
	s_waitcnt lgkmcnt(9)
	v_cvt_pk_bf16_f32 v31, v38, v39
	s_waitcnt lgkmcnt(6)
	v_cvt_pk_bf16_f32 v36, v42, v44
	v_cvt_pk_bf16_f32 v42, v43, v45
	s_waitcnt lgkmcnt(4)
	v_cvt_pk_bf16_f32 v37, v46, v48
	v_cvt_pk_bf16_f32 v43, v47, v49
	s_waitcnt lgkmcnt(2)
	v_cvt_pk_bf16_f32 v38, v56, v58
	v_cvt_pk_bf16_f32 v44, v57, v59
	s_waitcnt lgkmcnt(0)
	v_cvt_pk_bf16_f32 v39, v62, v68
	v_cvt_pk_bf16_f32 v45, v63, v69
	v_lshlrev_b32_e32 v46, 16, v50
	v_lshlrev_b32_e32 v47, 16, v54
	v_lshlrev_b32_e32 v48, 16, v67
	v_lshlrev_b32_e32 v49, 16, v70
	v_lshlrev_b32_e32 v56, 16, v71
	v_lshlrev_b32_e32 v57, 16, v25
	s_waitcnt vmcnt(1)
	v_lshlrev_b32_e32 v58, 16, v72
	s_waitcnt vmcnt(0)
	v_lshlrev_b32_e32 v59, 16, v73
	v_add_u32_e32 v25, 0x6000, v34
	v_mfma_f32_16x16x32_bf16 v[36:39], v[28:31], v[36:39], v[46:49]
	v_mfma_f32_16x16x32_bf16 v[28:31], v[28:31], v[42:45], v[56:59]
	s_nop 1
	ds_read2_b32 v[46:47], v25 offset0:96 offset1:112
	ds_read2_b32 v[48:49], v25 offset0:161 offset1:177
	ds_read2_b32 v[44:45], v32 offset0:34 offset1:35
	ds_read2_b32 v[56:57], v32 offset0:36 offset1:37
	ds_read2_b32 v[32:33], v32 offset0:38 offset1:39
	ds_read2_b32 v[58:59], v25 offset0:226 offset1:242
	v_add_u32_e32 v25, 0x6400, v34
	v_cvt_pk_bf16_f32 v42, v60, v61
	ds_read2_b32 v[60:61], v25 offset0:35 offset1:51
	ds_read2_b32 v[62:63], v25 offset0:100 offset1:116
	ds_read2_b32 v[68:69], v25 offset0:165 offset1:181
	ds_read2_b32 v[70:71], v25 offset0:230 offset1:246
	v_add_u32_e32 v25, 0x6800, v34
	ds_read2_b32 v[72:73], v25 offset0:39 offset1:55
	s_waitcnt lgkmcnt(8)
	v_cvt_pk_bf16_f32 v43, v44, v45
	s_waitcnt lgkmcnt(7)
	v_cvt_pk_bf16_f32 v44, v56, v57
	s_waitcnt lgkmcnt(6)
	v_cvt_pk_bf16_f32 v45, v32, v33
	v_cvt_pk_bf16_f32 v46, v46, v48
	v_cvt_pk_bf16_f32 v56, v47, v49
	s_waitcnt lgkmcnt(4)
	v_cvt_pk_bf16_f32 v47, v58, v60
	s_waitcnt lgkmcnt(2)
	v_cvt_pk_bf16_f32 v48, v62, v68
	s_waitcnt lgkmcnt(0)
	v_cvt_pk_bf16_f32 v49, v70, v72
	v_cvt_pk_bf16_f32 v57, v59, v61
	v_cvt_pk_bf16_f32 v58, v63, v69
	v_mfma_f32_16x16x32_bf16 v[36:39], v[42:45], v[46:49], v[36:39]
	v_cvt_pk_bf16_f32 v59, v71, v73
	v_add_lshl_u32 v33, v27, v40, 2
	v_add_u32_e32 v25, 0x8200, v33
	v_mfma_f32_16x16x32_bf16 v[28:31], v[42:45], v[56:59], v[28:31]
	v_or_b32_e32 v34, 16, v40
	s_nop 2
	ds_write2_b32 v25, v37, v38 offset0:65 offset1:130
	ds_write_b32 v33, v39 offset:34060
	v_add_u32_e32 v25, 0x8000, v33
	v_add_lshl_u32 v50, v27, v34, 2
	ds_write2_b32 v25, v36, v28 offset0:128 offset1:144
	v_add_u32_e32 v25, 0x8200, v50
	ds_write2_b32 v25, v29, v30 offset0:65 offset1:130
	ds_write_b32 v50, v31 offset:34060
	v_mad_u64_u32 v[24:25], s[0:1], v74, s69, v[24:25]
	ds_read_b128 v[28:31], v24 offset:49920
	ds_read_b128 v[36:39], v24 offset:49936
	ds_read_b128 v[42:45], v24 offset:50048
	ds_read_b128 v[46:49], v24 offset:50064
	ds_read_b128 v[56:59], v24 offset:50192
	s_waitcnt lgkmcnt(4)
	v_cvt_pk_bf16_f32 v28, v28, v29
	v_cvt_pk_bf16_f32 v29, v30, v31
	s_waitcnt lgkmcnt(3)
	v_cvt_pk_bf16_f32 v30, v36, v37
	v_cvt_pk_bf16_f32 v31, v38, v39
	s_waitcnt lgkmcnt(2)
	v_cvt_pk_bf16_f32 v42, v42, v43
	v_cvt_pk_bf16_f32 v43, v44, v45
	s_waitcnt lgkmcnt(1)
	v_cvt_pk_bf16_f32 v44, v46, v47
	v_cvt_pk_bf16_f32 v45, v48, v49
	ds_read_b128 v[46:49], v24 offset:50176
	v_mfma_f32_16x16x32_bf16 v[36:39], v[28:31], v[0:3], 0
	v_add_u32_e32 v25, 0x41, v27
	v_add_u32_e32 v54, v25, v40
	v_add_u32_e32 v24, 0x82, v27
	s_waitcnt lgkmcnt(0)
	v_cvt_pk_bf16_f32 v46, v46, v47
	v_cvt_pk_bf16_f32 v47, v48, v49
	v_cvt_pk_bf16_f32 v48, v56, v57
	v_cvt_pk_bf16_f32 v49, v58, v59
	v_mfma_f32_16x16x32_bf16 v[28:31], v[28:31], v[4:7], 0
	v_add_u32_e32 v33, 0x18600, v33
	v_add_u32_e32 v27, 0xc3, v27
	v_add_u32_e32 v32, s55, v53
	v_mfma_f32_16x16x32_bf16 v[36:39], v[42:45], v[8:11], v[36:39]
	v_add_u32_e32 v25, v25, v34
	v_lshl_add_u32 v25, v25, 2, v66
	s_mov_b32 s0, 0
	v_mfma_f32_16x16x32_bf16 v[28:31], v[42:45], v[12:15], v[28:31]
	v_add_u32_e32 v42, v24, v40
	v_add_u32_e32 v40, v27, v40
	v_add_u32_e32 v24, v24, v34
	v_mfma_f32_16x16x32_bf16 v[36:39], v[46:49], v[16:19], v[36:39]
	v_add_u32_e32 v27, v27, v34
	v_lshl_add_u32 v24, v24, 2, v66
	s_mov_b32 s1, s80
	v_mfma_f32_16x16x32_bf16 v[28:31], v[46:49], v[20:23], v[28:31]
	s_nop 3
	ds_write_b32 v33, v36
	v_lshl_add_u32 v33, v54, 2, v66
	ds_write_b32 v33, v37
	v_lshl_add_u32 v33, v42, 2, v66
	ds_write_b32 v33, v38
	v_lshl_add_u32 v33, v40, 2, v66
	ds_write_b32 v33, v39
	v_add_u32_e32 v33, 0x18600, v50
	ds_write_b32 v33, v28
	ds_write_b32 v24, v30
	v_lshl_add_u32 v24, v27, 2, v66
	v_ashrrev_i32_e32 v33, 31, v32
	ds_write_b32 v25, v29
	ds_write_b32 v24, v31
	v_lshl_add_u64 v[24:25], v[32:33], 1, s[30:31]
	v_lshl_add_u32 v27, v53, 2, s33
	v_and_b32_e32 v101, 7, v53
	s_add_i32 s12, s72, s80
	v_lshl_add_u32 v101, v101, 3, s12
	s_add_i32 s12, s72, s73
	s_add_i32 s12, s12, -1
	v_min_u32_e32 v101, s12, v101
	v_lshlrev_b32_e32 v101, 5, v101
	s_mov_b32 s12, s57
	s_mov_b32 s13, s60
	global_load_dword v100, v101, s[12:13]
	s_waitcnt lgkmcnt(0)
	s_barrier
	s_waitcnt vmcnt(0)
	s_cmp_eq_u32 s85, 0
	s_cbranch_scc1 .Lpct_b
	global_load_dword v106, v[104:105], off
